# P0 weight transposes: w_in and gate/up item loops de-serialized (16 element pairs / 32 loads in flight instead of one load+wait per element)
# speedup vs baseline: 1.0360x; 1.0303x over previous
; template <int MODE>
; DI void conv_item(const float* src, const float* src2, const float* rs, bf16_t* dst, int K, int Nsrc, int nblk, LAS float* scr, int item, int lane) {
;   const int kb = item / nblk, nb = item % nblk, k0 = 64 * kb, n0 = 32 * nb;
;   const int n = n0 + (lane & 31);
;   int col = n; float cs = 1.f; const float* s = src;
;   if (MODE == 0) {
;     if (n < 1024) { const int head = n >> 7, pp = n & 127, half = (pp >> 4) & 1, jj = pp >> 5, i = pp & 15; col = head * 128 + half * 64 + jj * 16 + i; if (n >= 512) cs = 0.08838834764831845f; }
;     else if (n >= 3072 && n < 4096) { const int c = (n - 3072) & 255, base = n - c; col = base + 64 * ((c >> 5) & 3) + 32 * (c >> 7) + 8 * ((c & 15) >> 2) + 4 * ((c >> 4) & 1) + (c & 3); }
;     else if ((n >= 2048 && n < 3072) || n >= 4608) { const int rho = n & 31; col = (n & ~31) + 8 * ((rho & 15) >> 2) + 4 * (rho >> 4) + (rho & 3); }
;   } else if (MODE == 3) {
;     const int rho = n & 31; col = (n & ~31) + 8 * ((rho & 15) >> 2) + 4 * (rho >> 4) + (rho & 3);
;   } else if (MODE == 1) {
;     const int c = n & 255, r7 = c & 127, rho = r7 & 31; col = (n >> 8) * 128 + (r7 & ~31) + 8 * ((rho & 15) >> 2) + 4 * (rho >> 4) + (rho & 3); if (c >> 7) s = src2;
;   }
;   const float* sp = s + (long)(k0 + (lane >> 5)) * Nsrc + col;
; #pragma unroll 8
;   for (int i = 0; i < 32; ++i) {
;     const int kk = 2 * i + (lane >> 5);
;     float w = sp[(long)(2 * i) * Nsrc] * cs;
;     if (rs) w *= rs[k0 + kk];
;     scr[kk * 33 + (lane & 31)] = w;
;   }
.LBB0_36:
	s_andn2_saveexec_b64 s[62:63], s[4:5]
	s_cbranch_execz .LBB0_56
	v_add_u16_e32 v6, 0xee00, v139
	v_mul_u32_u24_e32 v20, 0xba2f, v6
	v_lshrrev_b32_e32 v20, 23, v20
	v_mul_lo_u16_e32 v21, 0xb0, v20
	v_sub_u16_e32 v6, v6, v21
	v_lshlrev_b16_e32 v39, 6, v20
	v_lshlrev_b32_e32 v38, 5, v6
	v_lshlrev_b32_e32 v20, 4, v6
	v_and_b32_e32 v6, 4, v6
	v_and_b32_e32 v36, 0xf80, v20
	v_mov_b32_e32 v20, s13
	v_mov_b32_e32 v21, s11
	v_cmp_eq_u32_e32 vcc, 0, v6
	v_mov_b32_e32 v6, s12
	v_and_b32_e32 v37, 0x60, v38
	v_cndmask_b32_e32 v35, v20, v21, vcc
	v_mov_b32_e32 v20, s10
	v_cndmask_b32_e32 v34, v6, v20, vcc
	v_or_b32_e32 v6, v48, v39
	v_lshlrev_b32_e32 v6, 2, v6
	v_lshl_add_u64 v[20:21], s[8:9], 0, v[6:7]
	v_or_b32_e32 v6, v49, v39
	v_lshlrev_b32_e32 v6, 2, v6
	v_lshl_add_u64 v[22:23], s[8:9], 0, v[6:7]
	v_or_b32_e32 v6, v50, v39
	v_lshlrev_b32_e32 v6, 2, v6
	v_lshl_add_u64 v[24:25], s[8:9], 0, v[6:7]
	v_or_b32_e32 v6, v51, v39
	v_lshlrev_b32_e32 v6, 2, v6
	v_lshl_add_u64 v[26:27], s[8:9], 0, v[6:7]
	v_or_b32_e32 v6, v52, v39
	v_lshlrev_b32_e32 v6, 2, v6
	v_lshl_add_u64 v[28:29], s[8:9], 0, v[6:7]
	v_or_b32_e32 v6, v53, v39
	v_lshlrev_b32_e32 v6, 2, v6
	v_or_b32_e32 v57, v2, v39
	v_lshl_add_u64 v[30:31], s[8:9], 0, v[6:7]
	v_or_b32_e32 v6, v54, v39
	v_mul_u32_u24_e32 v58, 0xb00, v57
	v_lshlrev_b32_e32 v6, 2, v6
	v_or3_b32 v36, v55, v36, v37
	v_lshl_add_u64 v[32:33], s[8:9], 0, v[6:7]
	v_lshlrev_b32_e32 v6, 2, v58
	v_lshlrev_b32_e32 v36, 2, v36
	v_mov_b32_e32 v37, v7
	v_lshl_add_u64 v[36:37], v[6:7], 0, v[36:37]
	v_lshl_add_u64 v[34:35], v[34:35], 0, v[36:37]
	s_mov_b64 s[4:5], 0x16000
	v_lshlrev_b32_e32 v6, 2, v57
	v_lshl_add_u64 v[34:35], v[34:35], 0, s[4:5]
	v_lshl_add_u64 v[36:37], s[8:9], 0, v[6:7]
	s_mov_b64 s[64:65], 0
	v_mov_b32_e32 v6, v47
	s_andn2_b64 vcc, exec, s[34:35]
	s_cbranch_vccnz .LBB0_39
	v_add_co_u32_e32 v120, vcc, 0xfffea000, v34
	s_nop 1
	v_addc_co_u32_e32 v121, vcc, -1, v35, vcc
	s_mov_b64 s[4:5], 0x5800
	global_load_dword v88, v[120:121], off
	v_lshl_add_u64 v[120:121], v[120:121], 0, s[4:5]
	global_load_dword v89, v[120:121], off
	v_lshl_add_u64 v[120:121], v[120:121], 0, s[4:5]
	global_load_dword v90, v[120:121], off
	v_lshl_add_u64 v[120:121], v[120:121], 0, s[4:5]
	global_load_dword v91, v[120:121], off
	v_lshl_add_u64 v[120:121], v[120:121], 0, s[4:5]
	global_load_dword v92, v[120:121], off
	v_lshl_add_u64 v[120:121], v[120:121], 0, s[4:5]
	global_load_dword v93, v[120:121], off
	v_lshl_add_u64 v[120:121], v[120:121], 0, s[4:5]
	global_load_dword v94, v[120:121], off
	v_lshl_add_u64 v[120:121], v[120:121], 0, s[4:5]
	global_load_dword v95, v[120:121], off
	v_lshl_add_u64 v[120:121], v[120:121], 0, s[4:5]
	global_load_dword v96, v[120:121], off
	v_lshl_add_u64 v[120:121], v[120:121], 0, s[4:5]
	global_load_dword v97, v[120:121], off
	v_lshl_add_u64 v[120:121], v[120:121], 0, s[4:5]
	global_load_dword v98, v[120:121], off
	v_lshl_add_u64 v[120:121], v[120:121], 0, s[4:5]
	global_load_dword v99, v[120:121], off
	v_lshl_add_u64 v[120:121], v[120:121], 0, s[4:5]
	global_load_dword v100, v[120:121], off
	v_lshl_add_u64 v[120:121], v[120:121], 0, s[4:5]
	global_load_dword v101, v[120:121], off
	v_lshl_add_u64 v[120:121], v[120:121], 0, s[4:5]
	global_load_dword v102, v[120:121], off
	v_lshl_add_u64 v[120:121], v[120:121], 0, s[4:5]
	global_load_dword v103, v[120:121], off
	v_lshl_add_u64 v[120:121], v[120:121], 0, s[4:5]
	global_load_dword v104, v[36:37], off
	global_load_dword v105, v[36:37], off offset:8
	global_load_dword v106, v[36:37], off offset:16
	global_load_dword v107, v[36:37], off offset:24
	global_load_dword v108, v[36:37], off offset:32
	global_load_dword v109, v[36:37], off offset:40
	global_load_dword v110, v[36:37], off offset:48
	global_load_dword v111, v[36:37], off offset:56
	global_load_dword v112, v[36:37], off offset:64
	global_load_dword v113, v[36:37], off offset:72
	global_load_dword v114, v[36:37], off offset:80
	global_load_dword v115, v[36:37], off offset:88
	global_load_dword v116, v[36:37], off offset:96
	global_load_dword v117, v[36:37], off offset:104
	global_load_dword v118, v[36:37], off offset:112
	global_load_dword v119, v[36:37], off offset:120
	s_waitcnt vmcnt(15)
	v_mul_f32_e32 v88, v88, v104
	ds_write_b32 v6, v88
	s_waitcnt vmcnt(14)
	v_mul_f32_e32 v89, v89, v105
	ds_write_b32 v6, v89 offset:264
	s_waitcnt vmcnt(13)
	v_mul_f32_e32 v90, v90, v106
	ds_write_b32 v6, v90 offset:528
	s_waitcnt vmcnt(12)
	v_mul_f32_e32 v91, v91, v107
	ds_write_b32 v6, v91 offset:792
	s_waitcnt vmcnt(11)
	v_mul_f32_e32 v92, v92, v108
	ds_write_b32 v6, v92 offset:1056
	s_waitcnt vmcnt(10)
; template <int MODE>
; DI void conv_item(const float* src, const float* src2, const float* rs, bf16_t* dst, int K, int Nsrc, int nblk, LAS float* scr, int item, int lane) {
;     ...
; #pragma unroll 8
;   for (int i = 0; i < 32; ++i) {
;     const int kk = 2 * i + (lane >> 5);
;     float w = sp[(long)(2 * i) * Nsrc] * cs;
;     if (rs) w *= rs[k0 + kk];
;     scr[kk * 33 + (lane & 31)] = w;
;   }
	v_mul_f32_e32 v93, v93, v109
	ds_write_b32 v6, v93 offset:1320
	s_waitcnt vmcnt(9)
	v_mul_f32_e32 v94, v94, v110
	ds_write_b32 v6, v94 offset:1584
	s_waitcnt vmcnt(8)
	v_mul_f32_e32 v95, v95, v111
	ds_write_b32 v6, v95 offset:1848
	s_waitcnt vmcnt(7)
	v_mul_f32_e32 v96, v96, v112
	ds_write_b32 v6, v96 offset:2112
	s_waitcnt vmcnt(6)
	v_mul_f32_e32 v97, v97, v113
	ds_write_b32 v6, v97 offset:2376
	s_waitcnt vmcnt(5)
	v_mul_f32_e32 v98, v98, v114
	ds_write_b32 v6, v98 offset:2640
	s_waitcnt vmcnt(4)
	v_mul_f32_e32 v99, v99, v115
	ds_write_b32 v6, v99 offset:2904
	s_waitcnt vmcnt(3)
	v_mul_f32_e32 v100, v100, v116
	ds_write_b32 v6, v100 offset:3168
	s_waitcnt vmcnt(2)
	v_mul_f32_e32 v101, v101, v117
	ds_write_b32 v6, v101 offset:3432
	s_waitcnt vmcnt(1)
	v_mul_f32_e32 v102, v102, v118
	ds_write_b32 v6, v102 offset:3696
	s_waitcnt vmcnt(0)
	v_mul_f32_e32 v103, v103, v119
	ds_write_b32 v6, v103 offset:3960
	global_load_dword v88, v[120:121], off
	v_lshl_add_u64 v[120:121], v[120:121], 0, s[4:5]
	global_load_dword v89, v[120:121], off
	v_lshl_add_u64 v[120:121], v[120:121], 0, s[4:5]
	global_load_dword v90, v[120:121], off
	v_lshl_add_u64 v[120:121], v[120:121], 0, s[4:5]
	global_load_dword v91, v[120:121], off
	v_lshl_add_u64 v[120:121], v[120:121], 0, s[4:5]
	global_load_dword v92, v[120:121], off
	v_lshl_add_u64 v[120:121], v[120:121], 0, s[4:5]
	global_load_dword v93, v[120:121], off
	v_lshl_add_u64 v[120:121], v[120:121], 0, s[4:5]
	global_load_dword v94, v[120:121], off
	v_lshl_add_u64 v[120:121], v[120:121], 0, s[4:5]
	global_load_dword v95, v[120:121], off
	v_lshl_add_u64 v[120:121], v[120:121], 0, s[4:5]
	global_load_dword v96, v[120:121], off
	v_lshl_add_u64 v[120:121], v[120:121], 0, s[4:5]
	global_load_dword v97, v[120:121], off
	v_lshl_add_u64 v[120:121], v[120:121], 0, s[4:5]
	global_load_dword v98, v[120:121], off
	v_lshl_add_u64 v[120:121], v[120:121], 0, s[4:5]
	global_load_dword v99, v[120:121], off
	v_lshl_add_u64 v[120:121], v[120:121], 0, s[4:5]
	global_load_dword v100, v[120:121], off
	v_lshl_add_u64 v[120:121], v[120:121], 0, s[4:5]
	global_load_dword v101, v[120:121], off
	v_lshl_add_u64 v[120:121], v[120:121], 0, s[4:5]
	global_load_dword v102, v[120:121], off
	v_lshl_add_u64 v[120:121], v[120:121], 0, s[4:5]
	global_load_dword v103, v[120:121], off
	v_lshl_add_u64 v[120:121], v[120:121], 0, s[4:5]
	global_load_dword v104, v[36:37], off offset:128
	global_load_dword v105, v[36:37], off offset:136
	global_load_dword v106, v[36:37], off offset:144
	global_load_dword v107, v[36:37], off offset:152
	global_load_dword v108, v[36:37], off offset:160
	global_load_dword v109, v[36:37], off offset:168
	global_load_dword v110, v[36:37], off offset:176
	global_load_dword v111, v[36:37], off offset:184
	global_load_dword v112, v[36:37], off offset:192
	global_load_dword v113, v[36:37], off offset:200
	global_load_dword v114, v[36:37], off offset:208
	global_load_dword v115, v[36:37], off offset:216
	global_load_dword v116, v[36:37], off offset:224
	global_load_dword v117, v[36:37], off offset:232
	global_load_dword v118, v[36:37], off offset:240
	global_load_dword v119, v[36:37], off offset:248
	s_waitcnt vmcnt(15)
	v_mul_f32_e32 v88, v88, v104
	ds_write_b32 v6, v88 offset:4224
	s_waitcnt vmcnt(14)
	v_mul_f32_e32 v89, v89, v105
	ds_write_b32 v6, v89 offset:4488
	s_waitcnt vmcnt(13)
	v_mul_f32_e32 v90, v90, v106
	ds_write_b32 v6, v90 offset:4752
	s_waitcnt vmcnt(12)
	v_mul_f32_e32 v91, v91, v107
	ds_write_b32 v6, v91 offset:5016
	s_waitcnt vmcnt(11)
	v_mul_f32_e32 v92, v92, v108
	ds_write_b32 v6, v92 offset:5280
	s_waitcnt vmcnt(10)
	v_mul_f32_e32 v93, v93, v109
	ds_write_b32 v6, v93 offset:5544
	s_waitcnt vmcnt(9)
	v_mul_f32_e32 v94, v94, v110
	ds_write_b32 v6, v94 offset:5808
	s_waitcnt vmcnt(8)
	v_mul_f32_e32 v95, v95, v111
	ds_write_b32 v6, v95 offset:6072
	s_waitcnt vmcnt(7)
	v_mul_f32_e32 v96, v96, v112
	ds_write_b32 v6, v96 offset:6336
	s_waitcnt vmcnt(6)
	v_mul_f32_e32 v97, v97, v113
	ds_write_b32 v6, v97 offset:6600
	s_waitcnt vmcnt(5)
	v_mul_f32_e32 v98, v98, v114
	ds_write_b32 v6, v98 offset:6864
	s_waitcnt vmcnt(4)
	v_mul_f32_e32 v99, v99, v115
	ds_write_b32 v6, v99 offset:7128
	s_waitcnt vmcnt(3)
	v_mul_f32_e32 v100, v100, v116
	ds_write_b32 v6, v100 offset:7392
	s_waitcnt vmcnt(2)
	v_mul_f32_e32 v101, v101, v117
	ds_write_b32 v6, v101 offset:7656
	s_waitcnt vmcnt(1)
	v_mul_f32_e32 v102, v102, v118
	ds_write_b32 v6, v102 offset:7920
	s_waitcnt vmcnt(0)
	v_mul_f32_e32 v103, v103, v119
	ds_write_b32 v6, v103 offset:8184
	s_branch .LBB0_55

; template <int MODE>
; DI void conv_item(const float* src, const float* src2, const float* rs, bf16_t* dst, int K, int Nsrc, int nblk, LAS float* scr, int item, int lane) {
;     ...
;   const int n = n0 + (lane & 31);
;   int col = n; float cs = 1.f; const float* s = src;
;   if (MODE == 0) {
;     if (n < 1024) { const int head = n >> 7, pp = n & 127, half = (pp >> 4) & 1, jj = pp >> 5, i = pp & 15; col = head * 128 + half * 64 + jj * 16 + i; if (n >= 512) cs = 0.08838834764831845f; }
;     else if (n >= 3072 && n < 4096) { const int c = (n - 3072) & 255, base = n - c; col = base + 64 * ((c >> 5) & 3) + 32 * (c >> 7) + 8 * ((c & 15) >> 2) + 4 * ((c >> 4) & 1) + (c & 3); }
;     else if ((n >= 2048 && n < 3072) || n >= 4608) { const int rho = n & 31; col = (n & ~31) + 8 * ((rho & 15) >> 2) + 4 * (rho >> 4) + (rho & 3); }
;   } else if (MODE == 3) {
;     const int rho = n & 31; col = (n & ~31) + 8 * ((rho & 15) >> 2) + 4 * (rho >> 4) + (rho & 3);
;   } else if (MODE == 1) {
;     const int c = n & 255, r7 = c & 127, rho = r7 & 31; col = (n >> 8) * 128 + (r7 & ~31) + 8 * ((rho & 15) >> 2) + 4 * (rho >> 4) + (rho & 3); if (c >> 7) s = src2;
;   }
;   const float* sp = s + (long)(k0 + (lane >> 5)) * Nsrc + col;
; #pragma unroll 8
;   for (int i = 0; i < 32; ++i) {
;     const int kk = 2 * i + (lane >> 5);
;     float w = sp[(long)(2 * i) * Nsrc] * cs;
;     if (rs) w *= rs[k0 + kk];
;     scr[kk * 33 + (lane & 31)] = w;
;   }
.LBB0_79:
	s_or_saveexec_b64 s[0:1], s[4:5]
	v_mov_b32_e32 v21, 1.0
	s_xor_b64 exec, exec, s[0:1]
	v_lshlrev_b32_e32 v22, 4, v22
	v_and_b32_e32 v21, 0xffffff80, v6
	v_and_b32_e32 v22, 48, v22
	v_cmp_lt_i32_e32 vcc, s70, v23
	v_or3_b32 v36, v46, v21, v22
	s_nop 0
	v_cndmask_b32_e32 v21, 1.0, v56, vcc
	s_or_b64 exec, exec, s[0:1]
	v_lshlrev_b32_e32 v20, 6, v20
	v_ashrrev_i32_e32 v37, 31, v36
	v_or_b32_e32 v22, v48, v20
	v_or_b32_e32 v24, v49, v20
	v_or_b32_e32 v26, v50, v20
	v_or_b32_e32 v28, v51, v20
	v_or_b32_e32 v30, v52, v20
	v_or_b32_e32 v32, v53, v20
	v_or_b32_e32 v34, v54, v20
	v_or_b32_e32 v38, v2, v20
	v_lshlrev_b64 v[36:37], 2, v[36:37]
	v_ashrrev_i32_e32 v23, 31, v22
	v_ashrrev_i32_e32 v25, 31, v24
	v_ashrrev_i32_e32 v27, 31, v26
	v_ashrrev_i32_e32 v29, 31, v28
	v_ashrrev_i32_e32 v31, 31, v30
	v_ashrrev_i32_e32 v33, 31, v32
	v_ashrrev_i32_e32 v35, 31, v34
	v_ashrrev_i32_e32 v39, 31, v38
	v_mad_i64_i32 v[36:37], s[0:1], v38, s71, v[36:37]
	v_lshl_add_u64 v[22:23], v[22:23], 2, s[38:39]
	v_lshl_add_u64 v[24:25], v[24:25], 2, s[38:39]
	v_lshl_add_u64 v[26:27], v[26:27], 2, s[38:39]
	v_lshl_add_u64 v[28:29], v[28:29], 2, s[38:39]
	v_lshl_add_u64 v[30:31], v[30:31], 2, s[38:39]
	v_lshl_add_u64 v[32:33], v[32:33], 2, s[38:39]
	v_lshl_add_u64 v[34:35], v[34:35], 2, s[38:39]
	v_lshl_add_u64 v[36:37], s[40:41], 0, v[36:37]
	v_lshl_add_u64 v[38:39], v[38:39], 2, s[38:39]
	s_mov_b64 s[0:1], 0
	v_mov_b32_e32 v57, v47
	s_andn2_b64 vcc, exec, s[52:53]
	s_cbranch_vccnz .LBB0_83
	v_add_co_u32_e32 v120, vcc, 0xfffcc000, v36
	s_nop 1
	v_addc_co_u32_e32 v121, vcc, -1, v37, vcc
	s_mov_b64 s[4:5], 0xd000
	global_load_dword v88, v[120:121], off
	v_lshl_add_u64 v[120:121], v[120:121], 0, s[4:5]
	global_load_dword v89, v[120:121], off
	v_lshl_add_u64 v[120:121], v[120:121], 0, s[4:5]
	global_load_dword v90, v[120:121], off
	v_lshl_add_u64 v[120:121], v[120:121], 0, s[4:5]
	global_load_dword v91, v[120:121], off
	v_lshl_add_u64 v[120:121], v[120:121], 0, s[4:5]
	global_load_dword v92, v[120:121], off
	v_lshl_add_u64 v[120:121], v[120:121], 0, s[4:5]
	global_load_dword v93, v[120:121], off
	v_lshl_add_u64 v[120:121], v[120:121], 0, s[4:5]
	global_load_dword v94, v[120:121], off
	v_lshl_add_u64 v[120:121], v[120:121], 0, s[4:5]
	global_load_dword v95, v[120:121], off
	v_lshl_add_u64 v[120:121], v[120:121], 0, s[4:5]
	global_load_dword v96, v[120:121], off
	v_lshl_add_u64 v[120:121], v[120:121], 0, s[4:5]
	global_load_dword v97, v[120:121], off
	v_lshl_add_u64 v[120:121], v[120:121], 0, s[4:5]
	global_load_dword v98, v[120:121], off
	v_lshl_add_u64 v[120:121], v[120:121], 0, s[4:5]
	global_load_dword v99, v[120:121], off
	v_lshl_add_u64 v[120:121], v[120:121], 0, s[4:5]
	global_load_dword v100, v[120:121], off
	v_lshl_add_u64 v[120:121], v[120:121], 0, s[4:5]
	global_load_dword v101, v[120:121], off
	v_lshl_add_u64 v[120:121], v[120:121], 0, s[4:5]
	global_load_dword v102, v[120:121], off
	v_lshl_add_u64 v[120:121], v[120:121], 0, s[4:5]
	global_load_dword v103, v[120:121], off
	v_lshl_add_u64 v[120:121], v[120:121], 0, s[4:5]
	global_load_dword v104, v[38:39], off
	global_load_dword v105, v[38:39], off offset:8
	global_load_dword v106, v[38:39], off offset:16
	global_load_dword v107, v[38:39], off offset:24
	global_load_dword v108, v[38:39], off offset:32
	global_load_dword v109, v[38:39], off offset:40
	global_load_dword v110, v[38:39], off offset:48
	global_load_dword v111, v[38:39], off offset:56
	global_load_dword v112, v[38:39], off offset:64
	global_load_dword v113, v[38:39], off offset:72
	global_load_dword v114, v[38:39], off offset:80
	global_load_dword v115, v[38:39], off offset:88
	global_load_dword v116, v[38:39], off offset:96
	global_load_dword v117, v[38:39], off offset:104
	global_load_dword v118, v[38:39], off offset:112
	global_load_dword v119, v[38:39], off offset:120
	s_waitcnt vmcnt(15)
	v_mul_f32_e32 v88, v21, v88
	v_mul_f32_e32 v88, v88, v104
	ds_write_b32 v57, v88
	s_waitcnt vmcnt(14)
	v_mul_f32_e32 v89, v21, v89
	v_mul_f32_e32 v89, v89, v105
	ds_write_b32 v57, v89 offset:264
	s_waitcnt vmcnt(13)
	v_mul_f32_e32 v90, v21, v90
	v_mul_f32_e32 v90, v90, v106
	ds_write_b32 v57, v90 offset:528
	s_waitcnt vmcnt(12)
	v_mul_f32_e32 v91, v21, v91
	v_mul_f32_e32 v91, v91, v107
	ds_write_b32 v57, v91 offset:792
	s_waitcnt vmcnt(11)
	v_mul_f32_e32 v92, v21, v92
	v_mul_f32_e32 v92, v92, v108
	ds_write_b32 v57, v92 offset:1056
	s_waitcnt vmcnt(10)
	v_mul_f32_e32 v93, v21, v93
	v_mul_f32_e32 v93, v93, v109
	ds_write_b32 v57, v93 offset:1320
	s_waitcnt vmcnt(9)
	v_mul_f32_e32 v94, v21, v94
	v_mul_f32_e32 v94, v94, v110
	ds_write_b32 v57, v94 offset:1584
	s_waitcnt vmcnt(8)
	v_mul_f32_e32 v95, v21, v95
	v_mul_f32_e32 v95, v95, v111
	ds_write_b32 v57, v95 offset:1848
	s_waitcnt vmcnt(7)
	v_mul_f32_e32 v96, v21, v96
	v_mul_f32_e32 v96, v96, v112
	ds_write_b32 v57, v96 offset:2112
	s_waitcnt vmcnt(6)
; template <int MODE>
; DI void conv_item(const float* src, const float* src2, const float* rs, bf16_t* dst, int K, int Nsrc, int nblk, LAS float* scr, int item, int lane) {
;     ...
; #pragma unroll 8
;   for (int i = 0; i < 32; ++i) {
;     const int kk = 2 * i + (lane >> 5);
;     float w = sp[(long)(2 * i) * Nsrc] * cs;
;     if (rs) w *= rs[k0 + kk];
;     scr[kk * 33 + (lane & 31)] = w;
;   }
	v_mul_f32_e32 v97, v21, v97
	v_mul_f32_e32 v97, v97, v113
	ds_write_b32 v57, v97 offset:2376
	s_waitcnt vmcnt(5)
	v_mul_f32_e32 v98, v21, v98
	v_mul_f32_e32 v98, v98, v114
	ds_write_b32 v57, v98 offset:2640
	s_waitcnt vmcnt(4)
	v_mul_f32_e32 v99, v21, v99
	v_mul_f32_e32 v99, v99, v115
	ds_write_b32 v57, v99 offset:2904
	s_waitcnt vmcnt(3)
	v_mul_f32_e32 v100, v21, v100
	v_mul_f32_e32 v100, v100, v116
	ds_write_b32 v57, v100 offset:3168
	s_waitcnt vmcnt(2)
	v_mul_f32_e32 v101, v21, v101
	v_mul_f32_e32 v101, v101, v117
	ds_write_b32 v57, v101 offset:3432
	s_waitcnt vmcnt(1)
	v_mul_f32_e32 v102, v21, v102
	v_mul_f32_e32 v102, v102, v118
	ds_write_b32 v57, v102 offset:3696
	s_waitcnt vmcnt(0)
	v_mul_f32_e32 v103, v21, v103
	v_mul_f32_e32 v103, v103, v119
	ds_write_b32 v57, v103 offset:3960
	global_load_dword v88, v[120:121], off
	v_lshl_add_u64 v[120:121], v[120:121], 0, s[4:5]
	global_load_dword v89, v[120:121], off
	v_lshl_add_u64 v[120:121], v[120:121], 0, s[4:5]
	global_load_dword v90, v[120:121], off
	v_lshl_add_u64 v[120:121], v[120:121], 0, s[4:5]
	global_load_dword v91, v[120:121], off
	v_lshl_add_u64 v[120:121], v[120:121], 0, s[4:5]
	global_load_dword v92, v[120:121], off
	v_lshl_add_u64 v[120:121], v[120:121], 0, s[4:5]
	global_load_dword v93, v[120:121], off
	v_lshl_add_u64 v[120:121], v[120:121], 0, s[4:5]
	global_load_dword v94, v[120:121], off
	v_lshl_add_u64 v[120:121], v[120:121], 0, s[4:5]
	global_load_dword v95, v[120:121], off
	v_lshl_add_u64 v[120:121], v[120:121], 0, s[4:5]
	global_load_dword v96, v[120:121], off
	v_lshl_add_u64 v[120:121], v[120:121], 0, s[4:5]
	global_load_dword v97, v[120:121], off
	v_lshl_add_u64 v[120:121], v[120:121], 0, s[4:5]
	global_load_dword v98, v[120:121], off
	v_lshl_add_u64 v[120:121], v[120:121], 0, s[4:5]
	global_load_dword v99, v[120:121], off
	v_lshl_add_u64 v[120:121], v[120:121], 0, s[4:5]
	global_load_dword v100, v[120:121], off
	v_lshl_add_u64 v[120:121], v[120:121], 0, s[4:5]
	global_load_dword v101, v[120:121], off
	v_lshl_add_u64 v[120:121], v[120:121], 0, s[4:5]
	global_load_dword v102, v[120:121], off
	v_lshl_add_u64 v[120:121], v[120:121], 0, s[4:5]
	global_load_dword v103, v[120:121], off
	v_lshl_add_u64 v[120:121], v[120:121], 0, s[4:5]
	global_load_dword v104, v[38:39], off offset:128
	global_load_dword v105, v[38:39], off offset:136
	global_load_dword v106, v[38:39], off offset:144
	global_load_dword v107, v[38:39], off offset:152
	global_load_dword v108, v[38:39], off offset:160
	global_load_dword v109, v[38:39], off offset:168
	global_load_dword v110, v[38:39], off offset:176
	global_load_dword v111, v[38:39], off offset:184
	global_load_dword v112, v[38:39], off offset:192
	global_load_dword v113, v[38:39], off offset:200
	global_load_dword v114, v[38:39], off offset:208
	global_load_dword v115, v[38:39], off offset:216
	global_load_dword v116, v[38:39], off offset:224
	global_load_dword v117, v[38:39], off offset:232
	global_load_dword v118, v[38:39], off offset:240
	global_load_dword v119, v[38:39], off offset:248
	s_waitcnt vmcnt(15)
	v_mul_f32_e32 v88, v21, v88
	v_mul_f32_e32 v88, v88, v104
	ds_write_b32 v57, v88 offset:4224
	s_waitcnt vmcnt(14)
	v_mul_f32_e32 v89, v21, v89
	v_mul_f32_e32 v89, v89, v105
	ds_write_b32 v57, v89 offset:4488
	s_waitcnt vmcnt(13)
	v_mul_f32_e32 v90, v21, v90
	v_mul_f32_e32 v90, v90, v106
	ds_write_b32 v57, v90 offset:4752
	s_waitcnt vmcnt(12)
	v_mul_f32_e32 v91, v21, v91
	v_mul_f32_e32 v91, v91, v107
	ds_write_b32 v57, v91 offset:5016
	s_waitcnt vmcnt(11)
	v_mul_f32_e32 v92, v21, v92
	v_mul_f32_e32 v92, v92, v108
	ds_write_b32 v57, v92 offset:5280
	s_waitcnt vmcnt(10)
	v_mul_f32_e32 v93, v21, v93
	v_mul_f32_e32 v93, v93, v109
	ds_write_b32 v57, v93 offset:5544
	s_waitcnt vmcnt(9)
	v_mul_f32_e32 v94, v21, v94
	v_mul_f32_e32 v94, v94, v110
	ds_write_b32 v57, v94 offset:5808
	s_waitcnt vmcnt(8)
	v_mul_f32_e32 v95, v21, v95
	v_mul_f32_e32 v95, v95, v111
	ds_write_b32 v57, v95 offset:6072
	s_waitcnt vmcnt(7)
	v_mul_f32_e32 v96, v21, v96
	v_mul_f32_e32 v96, v96, v112
	ds_write_b32 v57, v96 offset:6336
	s_waitcnt vmcnt(6)
	v_mul_f32_e32 v97, v21, v97
	v_mul_f32_e32 v97, v97, v113
	ds_write_b32 v57, v97 offset:6600
	s_waitcnt vmcnt(5)
	v_mul_f32_e32 v98, v21, v98
	v_mul_f32_e32 v98, v98, v114
	ds_write_b32 v57, v98 offset:6864
	s_waitcnt vmcnt(4)
	v_mul_f32_e32 v99, v21, v99
	v_mul_f32_e32 v99, v99, v115
	ds_write_b32 v57, v99 offset:7128
	s_waitcnt vmcnt(3)
	v_mul_f32_e32 v100, v21, v100
	v_mul_f32_e32 v100, v100, v116
	ds_write_b32 v57, v100 offset:7392
	s_waitcnt vmcnt(2)
	v_mul_f32_e32 v101, v21, v101
	v_mul_f32_e32 v101, v101, v117
	ds_write_b32 v57, v101 offset:7656
	s_waitcnt vmcnt(1)
	v_mul_f32_e32 v102, v21, v102
	v_mul_f32_e32 v102, v102, v118
	ds_write_b32 v57, v102 offset:7920
	s_waitcnt vmcnt(0)
	v_mul_f32_e32 v103, v21, v103
	v_mul_f32_e32 v103, v103, v119
	ds_write_b32 v57, v103 offset:8184
	s_branch .LBB0_26
